# mixer phase unit order remapped the same way: each XCD processes the rows whose in-projection outputs it wrote (and feeds the rows its out-projection tiles read)
# baseline (speedup 1.0000x reference)
; __device__ __forceinline__ void mixer_phase(LAS unsigned char* lds, const bf16_t* U, const bf16_t* Gt, const bf16_t* UZ, const bf16_t* V, const float* conv_w, const float* sg_norm,
;                                             const bf16_t* WTR, const float* sg_b, bf16_t* Y, int vcu, int G) {
;     ...
;     for (int unit = vcu; unit < BATCH * 64 * 8; unit += G) {
;         const int g = unit & 7, cch = (unit >> 3) & 63, b = unit >> 9; const size_t r0 = (size_t)b * SEQ + cch * 128;
;         const int ch = 128 * g + 8 * c8; const size_t row = r0 + 4 * rg;
;         u32x4 ur[6], gv[4], vv[4], uz[4];
;         const bool halo0 = (cch == 0 && rg == 0);
; #pragma unroll
;         for (int i = 0; i < 4; ++i) vv[i] = *(const u32x4*)(V + (r0 + s) * D + 128 * g + 32 * qd + 8 * i);
; #pragma unroll
;         for (int i = 0; i < 6; ++i) { if (i < 2 && halo0) ur[i] = (u32x4){0u, 0u, 0u, 0u}; else ur[i] = *(const u32x4*)(U + (row + i - 2) * D + ch); }
.LBB0_283:
	s_and_b32 s100, s36, 31
	s_bfe_u32 s101, s36, 0x20008
	s_lshl_b32 s101, s101, 5
	s_or_b32 s100, s100, s101
	s_bfe_u32 s101, s36, 0x20005
	s_lshl_b32 s101, s101, 7
	s_or_b32 s100, s100, s101
	s_bfe_u32 s101, s36, 0x10007
	s_lshl_b32 s101, s101, 9
	s_or_b32 s100, s100, s101
	s_ashr_i32 s24, s100, 9
	s_bfe_u32 s30, s100, 0x60003
	s_ashr_i32 s25, s24, 31
	s_lshl_b64 s[26:27], s[24:25], 13
	s_lshl_b32 s14, s30, 7
	s_or_b32 s26, s26, s14
	v_mov_b32_e32 v99, s27
	v_or_b32_e32 v98, s26, v82
	s_and_b32 s40, s100, 7
	v_lshlrev_b64 v[2:3], 11, v[98:99]
	v_lshl_add_u64 v[4:5], s[64:65], 0, v[2:3]
	s_lshl_b32 s14, s40, 8
	v_lshl_add_u64 v[4:5], v[4:5], 0, s[14:15]
	v_lshl_add_u64 v[4:5], v[4:5], 0, v[96:97]
	global_load_dwordx4 v[58:61], v[4:5], off offset:48
	global_load_dwordx4 v[62:65], v[4:5], off offset:32
	global_load_dwordx4 v[66:69], v[4:5], off offset:16
	global_load_dwordx4 v[70:73], v[4:5], off
	s_lshl_b32 s37, s40, 7
	s_cmp_lg_u32 s30, 0
	v_or_b32_e32 v74, s37, v83
	v_mov_b32_e32 v103, s27
	v_or_b32_e32 v102, s26, v84
	s_cselect_b64 s[26:27], -1, 0
	s_or_b64 s[26:27], s[26:27], s[0:1]
	v_lshlrev_b64 v[4:5], 11, v[102:103]
	v_lshlrev_b32_e32 v86, 1, v74
	v_mov_b32_e32 v34, 0
	v_mov_b32_e32 v35, 0
	v_mov_b32_e32 v36, 0
	v_mov_b32_e32 v37, 0
	s_and_saveexec_b64 s[30:31], s[26:27]
	s_cbranch_execz .LBB0_285
	v_lshlrev_b64 v[6:7], 11, v[102:103]
	v_lshl_add_u64 v[6:7], s[60:61], 0, v[6:7]
	v_lshl_add_u64 v[6:7], v[6:7], 0, v[86:87]
	global_load_dwordx4 v[34:37], v[6:7], off offset:-4096
